# strategy 1 on the grid-barrier spin: s_sleep removed from the two steady-state generation-word poll loops (on v52)
# speedup vs baseline: 1.0055x; 1.0055x over previous
.LBB0_728:
	s_and_b32 s18, s24, 0xff
	s_mov_b64 s[16:17], -1
	s_cmp_lg_u32 s18, 0
	s_mov_b64 s[36:37], -1
	s_nop 0
	s_cbranch_scc0 .LBB0_731
	s_and_b64 vcc, exec, s[36:37]
	s_cbranch_vccz .LBB0_727
